# attention row-max chain (7.12): self-max canonicalise pairs around v_permlane32_swap and the +0 add dropped
# baseline (speedup 1.0000x reference)
.LBB0_542:
	v_add_u32_e32 v192, s8, v212
	ds_read_b64_tr_b16 v[178:179], v192 offset:24576
	ds_read_b64_tr_b16 v[180:181], v192 offset:25088
	s_waitcnt lgkmcnt(9)
	v_mfma_f32_32x32x16_f16 v[98:113], v[174:177], v[138:141], v[34:49]
	v_add_f32_e32 v82, v66, v67
	v_add_f32_e32 v82, v68, v82
	v_add_f32_e32 v82, v69, v82
	v_add_f32_e32 v82, v70, v82
	v_add_f32_e32 v82, v71, v82
	v_cvt_pk_f16_f32 v142, v66, v67
	v_cvt_pk_f16_f32 v143, v68, v69
	ds_read_b64_tr_b16 v[174:175], v192 offset:28672
	ds_read_b64_tr_b16 v[176:177], v192 offset:29184
	v_add_f32_e32 v66, v72, v82
	s_waitcnt lgkmcnt(10)
	v_mfma_f32_32x32x16_f16 v[98:113], v[166:169], v[130:133], v[98:113]
	v_add_f32_e32 v66, v73, v66
	v_add_f32_e32 v66, v74, v66
	v_add_f32_e32 v122, v75, v66
	v_cvt_pk_f16_f32 v144, v70, v71
	v_cvt_pk_f16_f32 v145, v72, v73
	ds_read_b64_tr_b16 v[66:67], v192 offset:25600
	ds_read_b64_tr_b16 v[68:69], v192 offset:26112
	s_waitcnt lgkmcnt(11)
	v_mfma_f32_32x32x16_f16 v[98:113], v[158:161], v[118:121], v[98:113]
	v_add_f32_e32 v70, v76, v122
	v_add_f32_e32 v70, v77, v70
	v_add_f32_e32 v70, v78, v70
	v_add_f32_e32 v122, v79, v70
	v_cvt_pk_f16_f32 v134, v74, v75
	v_cvt_pk_f16_f32 v135, v76, v77
	ds_read_b64_tr_b16 v[70:71], v192 offset:29696
	ds_read_b64_tr_b16 v[72:73], v192 offset:30208
	s_waitcnt lgkmcnt(12)
	v_mfma_f32_32x32x16_f16 v[98:113], v[150:153], v[114:117], v[98:113]
	v_add_f32_e32 v74, v80, v122
	v_add_f32_e32 v74, v81, v74
	v_add_f32_e32 v74, v50, v74
	v_add_f32_e32 v122, v51, v74
	v_cvt_pk_f16_f32 v136, v78, v79
	v_cvt_pk_f16_f32 v137, v80, v81
	ds_read_b64_tr_b16 v[74:75], v192 offset:26624
	ds_read_b64_tr_b16 v[76:77], v192 offset:27136
	s_waitcnt lgkmcnt(13)
	v_mfma_f32_32x32x16_f16 v[82:97], v[170:173], v[138:141], v[34:49]
	v_add_f32_e32 v78, v52, v122
	v_add_f32_e32 v78, v53, v78
	v_add_f32_e32 v78, v54, v78
	v_add_f32_e32 v78, v55, v78
	v_cvt_pk_f16_f32 v126, v50, v51
	v_cvt_pk_f16_f32 v127, v52, v53
	ds_read_b64_tr_b16 v[50:51], v192 offset:30720
	ds_read_b64_tr_b16 v[52:53], v192 offset:31232
	s_waitcnt lgkmcnt(14)
	v_mfma_f32_32x32x16_f16 v[82:97], v[162:165], v[130:133], v[82:97]
	v_add_f32_e32 v78, v56, v78
	v_add_f32_e32 v78, v57, v78
	v_add_f32_e32 v78, v58, v78
	v_add_f32_e32 v78, v59, v78
	v_cvt_pk_f16_f32 v128, v54, v55
	v_cvt_pk_f16_f32 v129, v56, v57
	ds_read_b64_tr_b16 v[54:55], v192 offset:27648
	ds_read_b64_tr_b16 v[56:57], v192 offset:28160
	s_waitcnt lgkmcnt(14)
	v_mfma_f32_32x32x16_f16 v[82:97], v[154:157], v[118:121], v[82:97]
	v_add_f32_e32 v78, v60, v78
	v_add_f32_e32 v78, v61, v78
	v_add_f32_e32 v78, v62, v78
	v_add_f32_e32 v78, v63, v78
	v_cvt_pk_f16_f32 v122, v58, v59
	v_cvt_pk_f16_f32 v123, v60, v61
	ds_read_b64_tr_b16 v[58:59], v192 offset:31744
	ds_read_b64_tr_b16 v[60:61], v192 offset:32256
	v_mfma_f32_32x32x16_f16 v[82:97], v[146:149], v[114:117], v[82:97]
	v_add_f32_e32 v78, v64, v78
	v_add_f32_e32 v78, v65, v78
	v_cvt_pk_f16_f32 v124, v62, v63
	v_cvt_pk_f16_f32 v125, v64, v65
	v_lshl_add_u64 v[62:63], v[188:189], 0, s[54:55]
	s_add_i32 s8, s11, s76
	s_mov_b32 s9, m0
	s_mov_b32 m0, s8
	s_nop 0
	global_load_lds_dwordx4 v[62:63], off
	s_mov_b32 m0, s9
	v_lshl_add_u64 v[62:63], v[186:187], 0, s[54:55]
	s_add_i32 s8, s30, s77
	s_mov_b32 s9, m0
	s_mov_b32 m0, s8
	s_nop 0
	global_load_lds_dwordx4 v[62:63], off
	s_mov_b32 m0, s9
	v_max_f32_e32 v62, v99, v99
	v_max_f32_e32 v63, v98, v98
	v_max_f32_e32 v62, v63, v62
	v_max3_f32 v63, v100, v101, v83
	v_max3_f32 v62, v62, v82, v84
	v_max3_f32 v62, v62, v85, v102
	v_max3_f32 v63, v63, v104, v105
	v_max3_f32 v62, v62, v103, v86
	v_max3_f32 v63, v63, v88, v89
	v_max3_f32 v62, v62, v87, v106
	v_max3_f32 v63, v63, v108, v109
	v_max3_f32 v62, v62, v107, v90
	v_max3_f32 v63, v63, v92, v93
	v_max3_f32 v62, v62, v91, v110
	v_max3_f32 v63, v63, v112, v113
	v_max3_f32 v62, v62, v111, v94
	v_max3_f32 v63, v63, v96, v97
	v_max3_f32 v62, v62, v95, v63
	v_mov_b32_e32 v63, v62
	s_nop 1
	v_permlane32_swap_b32_e32 v62, v63
	v_max_f32_e32 v62, v62, v63
	v_cmp_lt_f32_e32 vcc, s81, v62
	s_cmp_lg_u64 vcc, 0
	v_add_f32_e32 v193, v214, v78
	s_cselect_b64 s[8:9], -1, 0
	s_cbranch_vccnz .LBB0_552

.LBB0_547:
	v_add_u32_e32 v194, s11, v212
	ds_read_b64_tr_b16 v[150:151], v194 offset:24576
	ds_read_b64_tr_b16 v[152:153], v194 offset:25088
	s_add_i32 s8, s30, 0x2000
	s_cmpk_lg_i32 s30, 0x4000
	s_cselect_b32 s11, s8, 0
	s_waitcnt lgkmcnt(9)
	v_mfma_f32_32x32x16_f16 v[66:81], v[62:65], v[138:141], v[34:49]
	v_add_f32_e32 v50, v98, v99
	v_add_f32_e32 v50, v100, v50
	v_add_f32_e32 v50, v101, v50
	v_add_f32_e32 v50, v102, v50
	v_add_f32_e32 v50, v103, v50
	v_cvt_pk_f16_f32 v142, v98, v99
	v_cvt_pk_f16_f32 v143, v100, v101
	ds_read_b64_tr_b16 v[154:155], v194 offset:28672
	ds_read_b64_tr_b16 v[156:157], v194 offset:29184
	v_add_f32_e32 v50, v104, v50
	v_add_f32_e32 v50, v105, v50
	v_add_f32_e32 v50, v106, v50
	v_add_f32_e32 v122, v107, v50
	s_waitcnt lgkmcnt(10)
	v_mfma_f32_32x32x16_f16 v[66:81], v[178:181], v[130:133], v[66:81]
	v_cvt_pk_f16_f32 v144, v102, v103
	v_cvt_pk_f16_f32 v145, v104, v105
	ds_read_b64_tr_b16 v[98:99], v194 offset:25600
	ds_read_b64_tr_b16 v[100:101], v194 offset:26112
	s_waitcnt lgkmcnt(11)
	v_mfma_f32_32x32x16_f16 v[66:81], v[166:169], v[118:121], v[66:81]
	v_add_f32_e32 v102, v108, v122
	v_add_f32_e32 v102, v109, v102
	v_add_f32_e32 v102, v110, v102
	v_add_f32_e32 v122, v111, v102
	v_cvt_pk_f16_f32 v134, v106, v107
	v_cvt_pk_f16_f32 v135, v108, v109
	ds_read_b64_tr_b16 v[102:103], v194 offset:29696
	ds_read_b64_tr_b16 v[104:105], v194 offset:30208
	s_waitcnt lgkmcnt(12)
	v_mfma_f32_32x32x16_f16 v[66:81], v[158:161], v[114:117], v[66:81]
	v_add_f32_e32 v106, v112, v122
	v_add_f32_e32 v106, v113, v106
	v_add_f32_e32 v106, v82, v106
	v_add_f32_e32 v122, v83, v106
	v_cvt_pk_f16_f32 v136, v110, v111
	v_cvt_pk_f16_f32 v137, v112, v113
	ds_read_b64_tr_b16 v[106:107], v194 offset:26624
	ds_read_b64_tr_b16 v[108:109], v194 offset:27136
	s_waitcnt lgkmcnt(13)
	v_mfma_f32_32x32x16_f16 v[50:65], v[174:177], v[138:141], v[34:49]
	v_add_f32_e32 v110, v84, v122
	v_add_f32_e32 v110, v85, v110
	v_add_f32_e32 v110, v86, v110
	v_add_f32_e32 v110, v87, v110
	v_cvt_pk_f16_f32 v126, v82, v83
	v_cvt_pk_f16_f32 v127, v84, v85
	ds_read_b64_tr_b16 v[82:83], v194 offset:30720
	ds_read_b64_tr_b16 v[84:85], v194 offset:31232
	s_waitcnt lgkmcnt(14)
	v_mfma_f32_32x32x16_f16 v[50:65], v[170:173], v[130:133], v[50:65]
	v_add_f32_e32 v110, v88, v110
	v_add_f32_e32 v110, v89, v110
	v_add_f32_e32 v110, v90, v110
	v_add_f32_e32 v110, v91, v110
	v_cvt_pk_f16_f32 v128, v86, v87
	v_cvt_pk_f16_f32 v129, v88, v89
	ds_read_b64_tr_b16 v[86:87], v194 offset:27648
	ds_read_b64_tr_b16 v[88:89], v194 offset:28160
	s_waitcnt lgkmcnt(14)
	v_mfma_f32_32x32x16_f16 v[50:65], v[162:165], v[118:121], v[50:65]
	v_add_f32_e32 v110, v92, v110
	v_add_f32_e32 v110, v93, v110
	v_add_f32_e32 v110, v94, v110
	v_add_f32_e32 v110, v95, v110
	v_cvt_pk_f16_f32 v122, v90, v91
	v_cvt_pk_f16_f32 v123, v92, v93
	ds_read_b64_tr_b16 v[90:91], v194 offset:31744
	ds_read_b64_tr_b16 v[92:93], v194 offset:32256
	v_mfma_f32_32x32x16_f16 v[50:65], v[146:149], v[114:117], v[50:65]
	v_add_f32_e32 v110, v96, v110
	v_add_f32_e32 v110, v97, v110
	v_add_f32_e32 v110, 0, v110
	v_cvt_pk_f16_f32 v124, v94, v95
	v_cvt_pk_f16_f32 v125, v96, v97
	v_max_f32_e32 v94, v67, v67
	v_max_f32_e32 v95, v66, v66
	v_max_f32_e32 v94, v95, v94
	s_nop 3
	v_max3_f32 v95, v68, v69, v51
	v_max3_f32 v94, v94, v50, v52
	v_max3_f32 v94, v94, v53, v70
	v_max3_f32 v95, v95, v72, v73
	v_max3_f32 v94, v94, v71, v54
	v_max3_f32 v95, v95, v56, v57
	v_max3_f32 v94, v94, v55, v74
	v_max3_f32 v95, v95, v76, v77
	v_max3_f32 v94, v94, v75, v58
	v_max3_f32 v95, v95, v60, v61
	v_max3_f32 v94, v94, v59, v78
	v_max3_f32 v95, v95, v80, v81
	v_max3_f32 v94, v94, v79, v62
	v_max3_f32 v95, v95, v64, v65
	v_max3_f32 v94, v94, v63, v95
	v_mov_b32_e32 v95, v94
	s_nop 1
	v_permlane32_swap_b32_e32 v94, v95
	s_add_i32 s8, s30, s76
	s_mov_b32 s9, m0
	s_mov_b32 m0, s8
	s_nop 0
	global_load_lds_dwordx4 v[188:189], off
	s_mov_b32 m0, s9
	v_max_f32_e32 v94, v94, v95
	s_add_i32 s8, s11, s77
	s_mov_b32 s9, m0
	s_mov_b32 m0, s8
	s_nop 0
	global_load_lds_dwordx4 v[186:187], off
	s_mov_b32 m0, s9
	v_cmp_lt_f32_e32 vcc, s81, v94
	s_cmp_lg_u64 vcc, 0
	v_add_f32_e32 v214, v193, v110
	s_cselect_b64 s[8:9], -1, 0
	s_cbranch_vccnz .LBB0_555

.LBB0_562:
	v_add_f32_e32 v114, v214, v50
	v_max_f32_e32 v50, v83, v83
	v_max_f32_e32 v51, v82, v82
	v_max_f32_e32 v50, v51, v50
	s_nop 0
	v_max3_f32 v51, v84, v85, v35
	v_max3_f32 v50, v50, v34, v36
	v_max3_f32 v50, v50, v37, v86
	v_max3_f32 v51, v51, v88, v89
	v_max3_f32 v50, v50, v87, v38
	v_max3_f32 v51, v51, v40, v41
	v_max3_f32 v50, v50, v39, v90
	v_max3_f32 v51, v51, v92, v93
	v_max3_f32 v50, v50, v91, v42
	v_max3_f32 v51, v51, v44, v45
	v_max3_f32 v50, v50, v43, v94
	v_max3_f32 v51, v51, v96, v97
	v_max3_f32 v50, v50, v95, v46
	v_max3_f32 v51, v51, v48, v49
	v_max3_f32 v50, v50, v47, v51
	v_mov_b32_e32 v51, v50
	s_nop 1
	v_permlane32_swap_b32_e32 v50, v51
	v_max_f32_e32 v50, v50, v51
	v_cmp_lt_f32_e32 vcc, s81, v50
	s_cmp_lg_u64 vcc, 0
	s_cselect_b64 s[2:3], -1, 0
	s_cbranch_vccnz .LBB0_623

.LBB0_576:
	v_max_f32_e32 v62, v99, v99
	v_max_f32_e32 v63, v98, v98
	v_max_f32_e32 v62, v63, v62
	v_max3_f32 v63, v100, v101, v83
	v_max3_f32 v62, v62, v82, v84
	v_max3_f32 v62, v62, v85, v102
	v_max3_f32 v63, v63, v104, v105
	v_max3_f32 v62, v62, v103, v86
	v_max3_f32 v63, v63, v88, v89
	v_max3_f32 v62, v62, v87, v106
	v_max3_f32 v63, v63, v108, v109
	v_max3_f32 v62, v62, v107, v90
	v_max3_f32 v63, v63, v92, v93
	v_max3_f32 v62, v62, v91, v110
	v_max3_f32 v63, v63, v112, v113
	v_max3_f32 v62, v62, v111, v94
	v_max3_f32 v63, v63, v96, v97
	v_max3_f32 v62, v62, v95, v63
	v_mov_b32_e32 v63, v62
	s_nop 1
	v_permlane32_swap_b32_e32 v62, v63
	v_max_f32_e32 v62, v62, v63
	v_cmp_lt_f32_e32 vcc, s81, v62
	s_cmp_lg_u64 vcc, 0
	v_add_f32_e32 v214, v214, v78
	s_cselect_b64 s[4:5], -1, 0
	s_cbranch_vccnz .LBB0_617

.LBB0_594:
	v_add_f32_e32 v214, v214, v90
	v_max_f32_e32 v90, v67, v67
	v_max_f32_e32 v91, v66, v66
	v_max_f32_e32 v90, v91, v90
	v_max3_f32 v91, v68, v69, v51
	v_max3_f32 v90, v90, v50, v52
	v_max3_f32 v90, v90, v53, v70
	v_max3_f32 v91, v91, v72, v73
	v_max3_f32 v90, v90, v71, v54
	v_max3_f32 v91, v91, v56, v57
	v_max3_f32 v90, v90, v55, v74
	v_max3_f32 v91, v91, v76, v77
	v_max3_f32 v90, v90, v75, v58
	v_max3_f32 v91, v91, v60, v61
	v_max3_f32 v90, v90, v59, v78
	v_max3_f32 v91, v91, v80, v81
	v_max3_f32 v90, v90, v79, v62
	v_max3_f32 v91, v91, v64, v65
	v_max3_f32 v90, v90, v63, v91
	v_mov_b32_e32 v91, v90
	s_nop 1
	v_permlane32_swap_b32_e32 v90, v91
	v_max_f32_e32 v90, v90, v91
	v_cmp_lt_f32_e32 vcc, s81, v90
	s_cmp_lg_u64 vcc, 0
	s_cselect_b64 s[8:9], -1, 0
	s_cbranch_vccnz .LBB0_620
